# latent attention QK: the eight K-fragment LDS reads of a key tile issued together into free VGPRs, MFMAs on counted lgkmcnt
# baseline (speedup 1.0000x reference)
.LBB0_557:
	v_add_u32_e32 v109, s16, v240
	v_add_u32_e32 v108, v109, v241
	ds_read_b128 v[160:163], v108
	ds_read_b128 v[176:179], v108 offset:4608
	ds_read_b128 v[164:167], v108 offset:32
	ds_read_b128 v[180:183], v108 offset:4640
	ds_read_b128 v[168:171], v108 offset:64
	ds_read_b128 v[184:187], v108 offset:4672
	ds_read_b128 v[172:175], v108 offset:96
	ds_read_b128 v[188:191], v108 offset:4704
	s_cmp_ge_i32 s52, s36
	s_waitcnt lgkmcnt(7)
	v_mfma_f32_32x32x16_bf16 v[50:65], v[160:163], v[66:69], 0
	s_waitcnt lgkmcnt(6)
	v_mfma_f32_32x32x16_bf16 v[34:49], v[176:179], v[66:69], 0
	s_waitcnt lgkmcnt(5)
	v_mfma_f32_32x32x16_bf16 v[50:65], v[164:167], v[70:73], v[50:65]
	s_waitcnt lgkmcnt(4)
	v_mfma_f32_32x32x16_bf16 v[34:49], v[180:183], v[70:73], v[34:49]
	s_waitcnt lgkmcnt(3)
	v_mfma_f32_32x32x16_bf16 v[50:65], v[168:171], v[74:77], v[50:65]
	s_waitcnt lgkmcnt(2)
	v_mfma_f32_32x32x16_bf16 v[34:49], v[184:187], v[74:77], v[34:49]
	s_waitcnt lgkmcnt(1)
	v_mfma_f32_32x32x16_bf16 v[50:65], v[172:175], v[78:81], v[50:65]
	s_waitcnt lgkmcnt(0)
	v_mfma_f32_32x32x16_bf16 v[34:49], v[188:191], v[78:81], v[34:49]
	s_cbranch_scc1 .LBB0_564
	s_add_i32 s54, s44, s52
	s_cmp_lt_i32 s54, 2
	s_cbranch_scc1 .LBB0_560
	s_cmp_eq_u32 s54, 2
	s_cselect_b64 s[16:17], -1, 0
	s_cbranch_execz .LBB0_561
	s_branch .LBB0_562

.LBB0_564:
	s_nop 7
	v_max_f32_e32 v102, v51, v51
	v_max_f32_e32 v103, v50, v50
	v_max_f32_e32 v102, v103, v102
	v_max3_f32 v102, v102, v52, v53
	v_max3_f32 v102, v102, v54, v55
	v_max3_f32 v102, v102, v56, v57
	v_max3_f32 v102, v102, v58, v59
	v_max3_f32 v102, v102, v60, v61
	v_max3_f32 v102, v102, v62, v63
	v_max3_f32 v102, v102, v64, v65
	v_max3_f32 v102, v102, v34, v35
	v_max3_f32 v102, v102, v36, v37
	v_max3_f32 v102, v102, v38, v39
	v_max3_f32 v102, v102, v40, v41
	v_and_b32_e32 v103, 64, v226
	v_max3_f32 v102, v102, v42, v43
	v_xor_b32_e32 v104, 32, v226
	v_add_u32_e32 v105, 64, v103
	v_max3_f32 v102, v102, v44, v45
	v_cmp_lt_i32_e32 vcc, v104, v105
	v_max3_f32 v102, v102, v46, v47
	v_max3_f32 v102, v102, v48, v49
	v_cndmask_b32_e32 v103, v226, v104, vcc
	v_lshlrev_b32_e32 v110, 2, v103
	ds_bpermute_b32 v103, v110, v102
	v_add_u32_e32 v109, v109, v150
	s_andn2_b64 vcc, exec, s[14:15]
	s_waitcnt lgkmcnt(0)
	v_max3_f32 v107, v0, v102, v103
	v_sub_f32_e32 v118, v0, v107
	v_sub_f32_e32 v0, v50, v107
	v_exp_f32_e32 v119, v0
	v_sub_f32_e32 v0, v34, v107
	v_exp_f32_e32 v120, v0
	v_sub_f32_e32 v0, v51, v107
	v_sub_f32_e32 v34, v35, v107
	v_exp_f32_e32 v0, v0
	v_exp_f32_e32 v102, v34
	v_add_f32_e32 v103, v120, v119
	v_pk_add_f32 v[34:35], v[102:103], v[0:1]
	s_nop 0
	v_pk_add_f32 v[50:51], v[34:35], v[34:35] op_sel_hi:[0,1]
	v_sub_f32_e32 v34, v52, v107
	v_exp_f32_e32 v103, v34
	v_sub_f32_e32 v34, v36, v107
	v_exp_f32_e32 v121, v34
	v_sub_f32_e32 v34, v53, v107
	v_exp_f32_e32 v50, v34
	v_sub_f32_e32 v34, v37, v107
	v_exp_f32_e32 v34, v34
	v_add_f32_e32 v35, v121, v103
	v_pk_add_f32 v[36:37], v[34:35], v[50:51]
	v_sub_f32_e32 v35, v54, v107
	v_pk_add_f32 v[52:53], v[36:37], v[36:37] op_sel_hi:[0,1]
	v_exp_f32_e32 v51, v35
	v_sub_f32_e32 v35, v38, v107
	v_sub_f32_e32 v36, v55, v107
	v_exp_f32_e32 v35, v35
	v_exp_f32_e32 v52, v36
	v_sub_f32_e32 v36, v39, v107
	v_exp_f32_e32 v36, v36
	v_add_f32_e32 v37, v35, v51
	v_pk_add_f32 v[38:39], v[36:37], v[52:53]
	v_sub_f32_e32 v37, v56, v107
	v_pk_add_f32 v[54:55], v[38:39], v[38:39] op_sel_hi:[0,1]
	v_exp_f32_e32 v53, v37
	v_sub_f32_e32 v37, v40, v107
	v_sub_f32_e32 v38, v57, v107
	v_exp_f32_e32 v37, v37
	v_exp_f32_e32 v54, v38
	v_sub_f32_e32 v38, v41, v107
	v_exp_f32_e32 v112, v38
	v_add_f32_e32 v113, v37, v53
	v_cvt_pk_bf16_f32 v40, v35, v36
	v_pk_add_f32 v[38:39], v[112:113], v[54:55]
	s_nop 0
	v_pk_add_f32 v[56:57], v[38:39], v[38:39] op_sel_hi:[0,1]
	v_sub_f32_e32 v38, v58, v107
	v_exp_f32_e32 v55, v38
	v_sub_f32_e32 v38, v42, v107
	v_exp_f32_e32 v113, v38
	v_sub_f32_e32 v38, v59, v107
	v_exp_f32_e32 v56, v38
	v_sub_f32_e32 v38, v43, v107
	v_exp_f32_e32 v114, v38
	v_add_f32_e32 v115, v113, v55
	v_cvt_pk_bf16_f32 v41, v37, v112
	v_cvt_pk_bf16_f32 v42, v55, v56
	v_pk_add_f32 v[38:39], v[114:115], v[56:57]
	s_nop 0
	v_pk_add_f32 v[58:59], v[38:39], v[38:39] op_sel_hi:[0,1]
	v_sub_f32_e32 v38, v60, v107
	v_exp_f32_e32 v43, v38
	v_sub_f32_e32 v38, v44, v107
	v_exp_f32_e32 v57, v38
	v_sub_f32_e32 v38, v61, v107
	v_exp_f32_e32 v58, v38
	v_sub_f32_e32 v38, v45, v107
	v_exp_f32_e32 v116, v38
	v_add_f32_e32 v117, v57, v43
	v_cvt_pk_bf16_f32 v43, v43, v58
	v_pk_add_f32 v[38:39], v[116:117], v[58:59]
	s_nop 0
	v_pk_add_f32 v[44:45], v[38:39], v[38:39] op_sel_hi:[0,1]
	v_sub_f32_e32 v38, v62, v107
	v_exp_f32_e32 v59, v38
	v_sub_f32_e32 v38, v46, v107
	v_exp_f32_e32 v115, v38
	v_sub_f32_e32 v38, v63, v107
	v_exp_f32_e32 v44, v38
	v_sub_f32_e32 v38, v47, v107
	v_exp_f32_e32 v60, v38
	v_add_f32_e32 v61, v115, v59
	v_cvt_pk_bf16_f32 v35, v57, v116
	v_add_u32_e32 v58, 0x3000, v109
	v_pk_add_f32 v[38:39], v[60:61], v[44:45]
	v_cvt_pk_bf16_f32 v44, v59, v44
	v_pk_add_f32 v[46:47], v[38:39], v[38:39] op_sel_hi:[0,1]
	v_sub_f32_e32 v38, v64, v107
	v_exp_f32_e32 v45, v38
	v_sub_f32_e32 v38, v48, v107
	v_exp_f32_e32 v48, v38
	v_sub_f32_e32 v38, v65, v107
	v_exp_f32_e32 v46, v38
	v_sub_f32_e32 v38, v49, v107
	v_exp_f32_e32 v62, v38
	v_add_f32_e32 v63, v48, v45
	v_cvt_pk_bf16_f32 v45, v45, v46
	v_cvt_pk_bf16_f32 v49, v53, v54
	v_pk_add_f32 v[38:39], v[62:63], v[46:47]
	v_cvt_pk_bf16_f32 v46, v119, v0
	v_add_f32_e32 v106, v38, v39
	v_exp_f32_e32 v38, v118
	v_add_u32_e32 v0, 0x2000, v109
	v_cvt_pk_bf16_f32 v37, v48, v62
	v_cvt_pk_bf16_f32 v47, v103, v50
	v_cvt_pk_bf16_f32 v48, v51, v52
	ds_read2_b64 v[50:53], v0 offset0:128 offset1:130
	ds_read2_b64 v[54:57], v0 offset0:132 offset1:134
	v_pk_mul_f32 v[32:33], v[32:33], v[38:39] op_sel_hi:[1,0]
	v_pk_mul_f32 v[30:31], v[30:31], v[38:39] op_sel_hi:[1,0]
	v_pk_mul_f32 v[28:29], v[28:29], v[38:39] op_sel_hi:[1,0]
	v_pk_mul_f32 v[26:27], v[26:27], v[38:39] op_sel_hi:[1,0]
	v_pk_mul_f32 v[24:25], v[24:25], v[38:39] op_sel_hi:[1,0]
	v_pk_mul_f32 v[22:23], v[22:23], v[38:39] op_sel_hi:[1,0]
	v_pk_mul_f32 v[20:21], v[20:21], v[38:39] op_sel_hi:[1,0]
	v_pk_mul_f32 v[18:19], v[18:19], v[38:39] op_sel_hi:[1,0]
	v_pk_mul_f32 v[16:17], v[16:17], v[38:39] op_sel_hi:[1,0]
	v_pk_mul_f32 v[14:15], v[14:15], v[38:39] op_sel_hi:[1,0]
	s_waitcnt lgkmcnt(1)
	v_mfma_f32_32x32x16_bf16 v[18:33], v[50:53], v[46:49], v[18:33]
	ds_read2_b64 v[50:53], v58 offset0:192 offset1:194
	v_mul_f32_e64 v12, v12, v38
	v_mul_f32_e64 v13, v13, v38
	v_mul_f32_e64 v10, v10, v38
	v_mul_f32_e64 v11, v11, v38
	v_pk_mul_f32 v[8:9], v[8:9], v[38:39] op_sel_hi:[1,0]
	v_pk_mul_f32 v[6:7], v[6:7], v[38:39] op_sel_hi:[1,0]
	v_pk_mul_f32 v[4:5], v[4:5], v[38:39] op_sel_hi:[1,0]
	v_pk_mul_f32 v[2:3], v[2:3], v[38:39] op_sel_hi:[1,0]
	s_waitcnt lgkmcnt(1)
	v_mfma_f32_32x32x16_bf16 v[18:33], v[54:57], v[42:45], v[18:33]
	v_fmac_f32_e32 v106, v111, v38
	v_cvt_pk_bf16_f32 v38, v120, v102
	v_cvt_pk_bf16_f32 v39, v121, v34
	v_cvt_pk_bf16_f32 v34, v113, v114
	v_cvt_pk_bf16_f32 v36, v115, v60
	s_waitcnt lgkmcnt(0)
	v_mfma_f32_32x32x16_bf16 v[2:17], v[50:53], v[46:49], v[2:17]
	ds_read2_b64 v[46:49], v58 offset0:196 offset1:198
	s_waitcnt lgkmcnt(0)
	v_mfma_f32_32x32x16_bf16 v[2:17], v[46:49], v[42:45], v[2:17]
	ds_read2_b64 v[42:45], v0 offset0:136 offset1:138
	s_waitcnt lgkmcnt(0)
	v_mfma_f32_32x32x16_bf16 v[18:33], v[42:45], v[38:41], v[18:33]
	ds_read2_b64 v[42:45], v58 offset0:200 offset1:202
	s_waitcnt lgkmcnt(0)
	v_mfma_f32_32x32x16_bf16 v[2:17], v[42:45], v[38:41], v[2:17]
	ds_read2_b64 v[38:41], v0 offset0:140 offset1:142
	s_waitcnt lgkmcnt(0)
	v_mfma_f32_32x32x16_bf16 v[18:33], v[38:41], v[34:37], v[18:33]
	ds_read2_b64 v[38:41], v58 offset0:204 offset1:206
	s_waitcnt lgkmcnt(0)
	v_mfma_f32_32x32x16_bf16 v[2:17], v[38:41], v[34:37], v[2:17]
	s_cbranch_vccnz .LBB0_573
	ds_read_b128 v[160:163], v108 offset:18432
	ds_read_b128 v[176:179], v108 offset:23040
	ds_read_b128 v[164:167], v108 offset:18464
	ds_read_b128 v[180:183], v108 offset:23072
	ds_read_b128 v[168:171], v108 offset:18496
	ds_read_b128 v[184:187], v108 offset:23104
	ds_read_b128 v[172:175], v108 offset:18528
	ds_read_b128 v[188:191], v108 offset:23136
	s_cmp_ge_i32 s53, s36
	s_waitcnt lgkmcnt(7)
	v_mfma_f32_32x32x16_bf16 v[50:65], v[160:163], v[66:69], 0
	s_waitcnt lgkmcnt(6)
	v_mfma_f32_32x32x16_bf16 v[34:49], v[176:179], v[66:69], 0
	s_waitcnt lgkmcnt(5)
	v_mfma_f32_32x32x16_bf16 v[50:65], v[164:167], v[70:73], v[50:65]
	s_waitcnt lgkmcnt(4)
	v_mfma_f32_32x32x16_bf16 v[34:49], v[180:183], v[70:73], v[34:49]
	s_waitcnt lgkmcnt(3)
	v_mfma_f32_32x32x16_bf16 v[50:65], v[168:171], v[74:77], v[50:65]
	s_waitcnt lgkmcnt(2)
	v_mfma_f32_32x32x16_bf16 v[34:49], v[184:187], v[74:77], v[34:49]
	s_waitcnt lgkmcnt(1)
	v_mfma_f32_32x32x16_bf16 v[50:65], v[172:175], v[78:81], v[50:65]
	s_waitcnt lgkmcnt(0)
	v_mfma_f32_32x32x16_bf16 v[34:49], v[188:191], v[78:81], v[34:49]
	s_cbranch_scc1 .LBB0_572
	s_add_i32 s18, s44, s52
	s_add_i32 s18, s18, 1
	s_cmp_lt_i32 s18, 2
	s_cbranch_scc1 .LBB0_568
	s_cmp_eq_u32 s18, 2
	s_cselect_b64 s[14:15], -1, 0
	s_cbranch_execz .LBB0_569
	s_branch .LBB0_570
